# ple-gate epilogue: f16->f32 conversions run one step ahead of the multiplies (no wait-state pads)
# speedup vs baseline: 1.0030x; 1.0030x over previous
; __device__ __forceinline__ float sigmoidf_(float x) { return __builtin_amdgcn_rcpf(1.0f + __expf(-x)); }
; __device__ __forceinline__ f32x4 sig4(const f32x4 v) { return (f32x4){sigmoidf_(v[0]), sigmoidf_(v[1]), sigmoidf_(v[2]), sigmoidf_(v[3])}; }
;     __device__ __forceinline__ void ple_gate(f32x4 (&acc)[2][2][4][2], const GUnit& u, int wr, int wc, int fr, int fq) const {
;         const f16* ple = (const f16*)(ws + WS_PLE); const int grow0 = u.pm * 256 + wr * 64 + fr, gcol0 = u.pn * 256 + wc * 32 + 8 * fq;
;         u32x4 pw[2][4][2];
; #pragma unroll
;         for (int ai = 0; ai < 2; ++ai)
; #pragma unroll
;             for (int m = 0; m < 4; ++m)
; #pragma unroll
;                 for (int bj = 0; bj < 2; ++bj) pw[ai][m][bj] = *(const u32x4*)(ple + (size_t)(grow0 + ai * 128 + m * 16) * 1024 + gcol0 + bj * 128);
;         asm volatile("" ::: "memory");
.LBB0_380:
	s_lshl_b32 s8, s37, 8
	s_add_i32 s8, s8, s48
	v_or_b32_e32 v132, s8, v185
	s_lshl_b32 s8, s34, 8
	v_readlane_b32 s9, v251, 28
	s_or_b32 s8, s8, s9
	v_lshl_add_u32 v134, v35, 3, s8
	v_readlane_b32 s8, v252, 3
	v_readlane_b32 s9, v252, 4
	v_ashrrev_i32_e32 v135, 31, v134
	v_ashrrev_i32_e32 v133, 31, v132
	s_mov_b32 s98, 0xbfb8aa3b
	v_lshl_add_u64 v[134:135], v[134:135], 1, s[8:9]
	v_lshlrev_b64 v[132:133], 11, v[132:133]
	v_lshl_add_u64 v[132:133], v[134:135], 0, v[132:133]
	global_load_dwordx4 v[136:139], v[132:133], off
	global_load_dwordx4 v[140:143], v[132:133], off offset:256
	v_add_co_u32_e32 v134, vcc, 0x8000, v132
	v_addc_co_u32_e32 v135, vcc, 0, v133, vcc
	global_load_dwordx4 v[144:147], v[134:135], off
	global_load_dwordx4 v[148:151], v[134:135], off offset:256
	v_add_co_u32_e32 v134, vcc, 0x10000, v132
	v_addc_co_u32_e32 v135, vcc, 0, v133, vcc
	global_load_dwordx4 v[152:155], v[134:135], off
	global_load_dwordx4 v[156:159], v[134:135], off offset:256
	v_add_co_u32_e32 v134, vcc, 0x18000, v132
	v_addc_co_u32_e32 v135, vcc, 0, v133, vcc
	global_load_dwordx4 v[160:163], v[134:135], off
	global_load_dwordx4 v[164:167], v[134:135], off offset:256
	v_add_co_u32_e32 v134, vcc, 0x40000, v132
	v_addc_co_u32_e32 v135, vcc, 0, v133, vcc
	global_load_dwordx4 v[168:171], v[134:135], off
	global_load_dwordx4 v[172:175], v[134:135], off offset:256
	v_add_co_u32_e32 v134, vcc, 0x48000, v132
	v_addc_co_u32_e32 v135, vcc, 0, v133, vcc
	global_load_dwordx4 v[176:179], v[134:135], off
	global_load_dwordx4 v[180:183], v[134:135], off offset:256
	v_add_co_u32_e32 v134, vcc, 0x50000, v132
	v_addc_co_u32_e32 v135, vcc, 0, v133, vcc
	global_load_dwordx4 v[190:193], v[134:135], off
	global_load_dwordx4 v[198:201], v[134:135], off offset:256
	v_add_co_u32_e32 v134, vcc, 0x58000, v132
	v_addc_co_u32_e32 v135, vcc, 0, v133, vcc
	global_load_dwordx4 v[204:207], v[134:135], off
	global_load_dwordx4 v[208:211], v[134:135], off offset:256
	v_pk_mul_f32 v[128:129], v[128:129], s[98:99] op_sel_hi:[1,0]
	v_pk_mul_f32 v[130:131], v[130:131], s[98:99] op_sel_hi:[1,0]
	v_pk_mul_f32 v[124:125], v[124:125], s[98:99] op_sel_hi:[1,0]
	v_pk_mul_f32 v[126:127], v[126:127], s[98:99] op_sel_hi:[1,0]
	v_exp_f32_e32 v128, v128
	v_exp_f32_e32 v124, v124
	v_exp_f32_e32 v129, v129
	v_exp_f32_e32 v125, v125
	v_exp_f32_e32 v130, v130
	v_exp_f32_e32 v126, v126
	v_exp_f32_e32 v131, v131
	v_exp_f32_e32 v127, v127
	v_pk_add_f32 v[128:129], v[128:129], 1.0 op_sel_hi:[1,0]
	v_pk_add_f32 v[130:131], v[130:131], 1.0 op_sel_hi:[1,0]
	v_pk_add_f32 v[124:125], v[124:125], 1.0 op_sel_hi:[1,0]
	v_pk_add_f32 v[126:127], v[126:127], 1.0 op_sel_hi:[1,0]
	v_rcp_f32_e32 v128, v128
	v_rcp_f32_e32 v124, v124
	v_rcp_f32_e32 v129, v129
	v_rcp_f32_e32 v125, v125
	v_rcp_f32_e32 v130, v130
	v_rcp_f32_e32 v126, v126
	v_rcp_f32_e32 v131, v131
	v_rcp_f32_e32 v127, v127
	v_pk_mul_f32 v[120:121], v[120:121], s[98:99] op_sel_hi:[1,0]
	v_pk_mul_f32 v[122:123], v[122:123], s[98:99] op_sel_hi:[1,0]
	v_pk_mul_f32 v[116:117], v[116:117], s[98:99] op_sel_hi:[1,0]
	v_pk_mul_f32 v[118:119], v[118:119], s[98:99] op_sel_hi:[1,0]
	v_exp_f32_e32 v120, v120
	v_exp_f32_e32 v116, v116
	v_exp_f32_e32 v121, v121
	v_exp_f32_e32 v117, v117
	v_exp_f32_e32 v122, v122
	v_exp_f32_e32 v118, v118
	v_exp_f32_e32 v123, v123
	v_exp_f32_e32 v119, v119
	v_pk_add_f32 v[120:121], v[120:121], 1.0 op_sel_hi:[1,0]
	v_pk_add_f32 v[122:123], v[122:123], 1.0 op_sel_hi:[1,0]
	v_pk_add_f32 v[116:117], v[116:117], 1.0 op_sel_hi:[1,0]
	v_pk_add_f32 v[118:119], v[118:119], 1.0 op_sel_hi:[1,0]
	v_rcp_f32_e32 v120, v120
	v_rcp_f32_e32 v116, v116
	v_rcp_f32_e32 v121, v121
	v_rcp_f32_e32 v117, v117
	v_rcp_f32_e32 v122, v122
	v_rcp_f32_e32 v118, v118
	v_rcp_f32_e32 v123, v123
	v_rcp_f32_e32 v119, v119
	v_pk_mul_f32 v[112:113], v[112:113], s[98:99] op_sel_hi:[1,0]
	v_pk_mul_f32 v[114:115], v[114:115], s[98:99] op_sel_hi:[1,0]
	v_pk_mul_f32 v[108:109], v[108:109], s[98:99] op_sel_hi:[1,0]
	v_pk_mul_f32 v[110:111], v[110:111], s[98:99] op_sel_hi:[1,0]
	v_exp_f32_e32 v112, v112
	v_exp_f32_e32 v108, v108
	v_exp_f32_e32 v113, v113
	v_exp_f32_e32 v109, v109
	v_exp_f32_e32 v114, v114
	v_exp_f32_e32 v110, v110
	v_exp_f32_e32 v115, v115
	v_exp_f32_e32 v111, v111
	v_pk_add_f32 v[112:113], v[112:113], 1.0 op_sel_hi:[1,0]
	v_pk_add_f32 v[114:115], v[114:115], 1.0 op_sel_hi:[1,0]
	v_pk_add_f32 v[108:109], v[108:109], 1.0 op_sel_hi:[1,0]
	v_pk_add_f32 v[110:111], v[110:111], 1.0 op_sel_hi:[1,0]
	v_rcp_f32_e32 v112, v112
	v_rcp_f32_e32 v108, v108
	v_rcp_f32_e32 v113, v113
	v_rcp_f32_e32 v109, v109
	v_rcp_f32_e32 v114, v114
	v_rcp_f32_e32 v110, v110
	v_rcp_f32_e32 v115, v115
	v_rcp_f32_e32 v111, v111
	v_pk_mul_f32 v[104:105], v[104:105], s[98:99] op_sel_hi:[1,0]
	v_pk_mul_f32 v[106:107], v[106:107], s[98:99] op_sel_hi:[1,0]
	v_pk_mul_f32 v[100:101], v[100:101], s[98:99] op_sel_hi:[1,0]
	v_pk_mul_f32 v[102:103], v[102:103], s[98:99] op_sel_hi:[1,0]
	v_exp_f32_e32 v104, v104
	v_exp_f32_e32 v100, v100
	v_exp_f32_e32 v105, v105
	v_exp_f32_e32 v101, v101
	v_exp_f32_e32 v106, v106
	v_exp_f32_e32 v102, v102
	v_exp_f32_e32 v107, v107
	v_exp_f32_e32 v103, v103
	v_pk_add_f32 v[104:105], v[104:105], 1.0 op_sel_hi:[1,0]
	v_pk_add_f32 v[106:107], v[106:107], 1.0 op_sel_hi:[1,0]
	v_pk_add_f32 v[100:101], v[100:101], 1.0 op_sel_hi:[1,0]
	v_pk_add_f32 v[102:103], v[102:103], 1.0 op_sel_hi:[1,0]
	v_rcp_f32_e32 v104, v104
	v_rcp_f32_e32 v100, v100
	v_rcp_f32_e32 v105, v105
	v_rcp_f32_e32 v101, v101
	v_rcp_f32_e32 v106, v106
	v_rcp_f32_e32 v102, v102
	v_rcp_f32_e32 v107, v107
	v_rcp_f32_e32 v103, v103
	v_pk_mul_f32 v[96:97], v[96:97], s[98:99] op_sel_hi:[1,0]
; __device__ __forceinline__ float sigmoidf_(float x) { return __builtin_amdgcn_rcpf(1.0f + __expf(-x)); }
; __device__ __forceinline__ f32x4 sig4(const f32x4 v) { return (f32x4){sigmoidf_(v[0]), sigmoidf_(v[1]), sigmoidf_(v[2]), sigmoidf_(v[3])}; }
;     __device__ __forceinline__ void ple_gate(f32x4 (&acc)[2][2][4][2], const GUnit& u, int wr, int wc, int fr, int fq) const {
;     ...
; #pragma unroll
;         for (int ai = 0; ai < 2; ++ai)
; #pragma unroll
;             for (int m = 0; m < 4; ++m)
; #pragma unroll
;                 for (int bj = 0; bj < 2; ++bj) { f32x4 p0, p1; unpk8(pw[ai][m][bj], p0, p1); acc[ai][bj][m][0] = sig4(acc[ai][bj][m][0]) * p0; acc[ai][bj][m][1] = sig4(acc[ai][bj][m][1]) * p1; }
	v_pk_mul_f32 v[98:99], v[98:99], s[98:99] op_sel_hi:[1,0]
	v_pk_mul_f32 v[92:93], v[92:93], s[98:99] op_sel_hi:[1,0]
	v_pk_mul_f32 v[94:95], v[94:95], s[98:99] op_sel_hi:[1,0]
	v_exp_f32_e32 v96, v96
	v_exp_f32_e32 v92, v92
	v_exp_f32_e32 v97, v97
	v_exp_f32_e32 v93, v93
	v_exp_f32_e32 v98, v98
	v_exp_f32_e32 v94, v94
	v_exp_f32_e32 v99, v99
	v_exp_f32_e32 v95, v95
	v_pk_add_f32 v[96:97], v[96:97], 1.0 op_sel_hi:[1,0]
	v_pk_add_f32 v[98:99], v[98:99], 1.0 op_sel_hi:[1,0]
	v_pk_add_f32 v[92:93], v[92:93], 1.0 op_sel_hi:[1,0]
	v_pk_add_f32 v[94:95], v[94:95], 1.0 op_sel_hi:[1,0]
	v_rcp_f32_e32 v96, v96
	v_rcp_f32_e32 v92, v92
	v_rcp_f32_e32 v97, v97
	v_rcp_f32_e32 v93, v93
	v_rcp_f32_e32 v98, v98
	v_rcp_f32_e32 v94, v94
	v_rcp_f32_e32 v99, v99
	v_rcp_f32_e32 v95, v95
	v_pk_mul_f32 v[88:89], v[88:89], s[98:99] op_sel_hi:[1,0]
	v_pk_mul_f32 v[90:91], v[90:91], s[98:99] op_sel_hi:[1,0]
	v_pk_mul_f32 v[84:85], v[84:85], s[98:99] op_sel_hi:[1,0]
	v_pk_mul_f32 v[86:87], v[86:87], s[98:99] op_sel_hi:[1,0]
	v_exp_f32_e32 v88, v88
	v_exp_f32_e32 v84, v84
	v_exp_f32_e32 v89, v89
	v_exp_f32_e32 v85, v85
	v_exp_f32_e32 v90, v90
	v_exp_f32_e32 v86, v86
	v_exp_f32_e32 v91, v91
	v_exp_f32_e32 v87, v87
	v_pk_add_f32 v[88:89], v[88:89], 1.0 op_sel_hi:[1,0]
	v_pk_add_f32 v[90:91], v[90:91], 1.0 op_sel_hi:[1,0]
	v_pk_add_f32 v[84:85], v[84:85], 1.0 op_sel_hi:[1,0]
	v_pk_add_f32 v[86:87], v[86:87], 1.0 op_sel_hi:[1,0]
	v_rcp_f32_e32 v88, v88
	v_rcp_f32_e32 v84, v84
	v_rcp_f32_e32 v89, v89
	v_rcp_f32_e32 v85, v85
	v_rcp_f32_e32 v90, v90
	v_rcp_f32_e32 v86, v86
	v_rcp_f32_e32 v91, v91
	v_rcp_f32_e32 v87, v87
	v_pk_mul_f32 v[80:81], v[80:81], s[98:99] op_sel_hi:[1,0]
	v_pk_mul_f32 v[82:83], v[82:83], s[98:99] op_sel_hi:[1,0]
	v_pk_mul_f32 v[76:77], v[76:77], s[98:99] op_sel_hi:[1,0]
	v_pk_mul_f32 v[78:79], v[78:79], s[98:99] op_sel_hi:[1,0]
	v_exp_f32_e32 v80, v80
	v_exp_f32_e32 v76, v76
	v_exp_f32_e32 v81, v81
	v_exp_f32_e32 v77, v77
	v_exp_f32_e32 v82, v82
	v_exp_f32_e32 v78, v78
	v_exp_f32_e32 v83, v83
	v_exp_f32_e32 v79, v79
	v_pk_add_f32 v[80:81], v[80:81], 1.0 op_sel_hi:[1,0]
	v_pk_add_f32 v[82:83], v[82:83], 1.0 op_sel_hi:[1,0]
	v_pk_add_f32 v[76:77], v[76:77], 1.0 op_sel_hi:[1,0]
	v_pk_add_f32 v[78:79], v[78:79], 1.0 op_sel_hi:[1,0]
	v_rcp_f32_e32 v80, v80
	v_rcp_f32_e32 v76, v76
	v_rcp_f32_e32 v81, v81
	v_rcp_f32_e32 v77, v77
	v_rcp_f32_e32 v82, v82
	v_rcp_f32_e32 v78, v78
	v_rcp_f32_e32 v83, v83
	v_rcp_f32_e32 v79, v79
	v_pk_mul_f32 v[72:73], v[72:73], s[98:99] op_sel_hi:[1,0]
	v_pk_mul_f32 v[74:75], v[74:75], s[98:99] op_sel_hi:[1,0]
	v_pk_mul_f32 v[68:69], v[68:69], s[98:99] op_sel_hi:[1,0]
	v_pk_mul_f32 v[70:71], v[70:71], s[98:99] op_sel_hi:[1,0]
	v_exp_f32_e32 v72, v72
	v_exp_f32_e32 v68, v68
	v_exp_f32_e32 v73, v73
	v_exp_f32_e32 v69, v69
	v_exp_f32_e32 v74, v74
	v_exp_f32_e32 v70, v70
	v_exp_f32_e32 v75, v75
	v_exp_f32_e32 v71, v71
	v_pk_add_f32 v[72:73], v[72:73], 1.0 op_sel_hi:[1,0]
	v_pk_add_f32 v[74:75], v[74:75], 1.0 op_sel_hi:[1,0]
	v_pk_add_f32 v[68:69], v[68:69], 1.0 op_sel_hi:[1,0]
	v_pk_add_f32 v[70:71], v[70:71], 1.0 op_sel_hi:[1,0]
	v_rcp_f32_e32 v72, v72
	v_rcp_f32_e32 v68, v68
	v_rcp_f32_e32 v73, v73
	v_rcp_f32_e32 v69, v69
	v_rcp_f32_e32 v74, v74
	v_rcp_f32_e32 v70, v70
	v_rcp_f32_e32 v75, v75
	v_rcp_f32_e32 v71, v71
	v_pk_mul_f32 v[64:65], v[64:65], s[98:99] op_sel_hi:[1,0]
	v_pk_mul_f32 v[66:67], v[66:67], s[98:99] op_sel_hi:[1,0]
	v_pk_mul_f32 v[60:61], v[60:61], s[98:99] op_sel_hi:[1,0]
	v_pk_mul_f32 v[62:63], v[62:63], s[98:99] op_sel_hi:[1,0]
	v_exp_f32_e32 v64, v64
	v_exp_f32_e32 v60, v60
	v_exp_f32_e32 v65, v65
	v_exp_f32_e32 v61, v61
	v_exp_f32_e32 v66, v66
	v_exp_f32_e32 v62, v62
	v_exp_f32_e32 v67, v67
	v_exp_f32_e32 v63, v63
	v_pk_add_f32 v[64:65], v[64:65], 1.0 op_sel_hi:[1,0]
	v_pk_add_f32 v[66:67], v[66:67], 1.0 op_sel_hi:[1,0]
	v_pk_add_f32 v[60:61], v[60:61], 1.0 op_sel_hi:[1,0]
	v_pk_add_f32 v[62:63], v[62:63], 1.0 op_sel_hi:[1,0]
	v_rcp_f32_e32 v64, v64
	v_rcp_f32_e32 v60, v60
	v_rcp_f32_e32 v65, v65
	v_rcp_f32_e32 v61, v61
	v_rcp_f32_e32 v66, v66
	v_rcp_f32_e32 v62, v62
	v_rcp_f32_e32 v67, v67
	v_rcp_f32_e32 v63, v63
	v_pk_mul_f32 v[56:57], v[56:57], s[98:99] op_sel_hi:[1,0]
	v_pk_mul_f32 v[58:59], v[58:59], s[98:99] op_sel_hi:[1,0]
	v_pk_mul_f32 v[52:53], v[52:53], s[98:99] op_sel_hi:[1,0]
	v_pk_mul_f32 v[54:55], v[54:55], s[98:99] op_sel_hi:[1,0]
	v_exp_f32_e32 v56, v56
	v_exp_f32_e32 v52, v52
	v_exp_f32_e32 v57, v57
	v_exp_f32_e32 v53, v53
	v_exp_f32_e32 v58, v58
	v_exp_f32_e32 v54, v54
	v_exp_f32_e32 v59, v59
	v_exp_f32_e32 v55, v55
	v_pk_add_f32 v[56:57], v[56:57], 1.0 op_sel_hi:[1,0]
	v_pk_add_f32 v[58:59], v[58:59], 1.0 op_sel_hi:[1,0]
	v_pk_add_f32 v[52:53], v[52:53], 1.0 op_sel_hi:[1,0]
	v_pk_add_f32 v[54:55], v[54:55], 1.0 op_sel_hi:[1,0]
	v_rcp_f32_e32 v56, v56
	v_rcp_f32_e32 v52, v52
	v_rcp_f32_e32 v57, v57
	v_rcp_f32_e32 v53, v53
	v_rcp_f32_e32 v58, v58
	v_rcp_f32_e32 v54, v54
	v_rcp_f32_e32 v59, v59
	v_rcp_f32_e32 v55, v55
	v_pk_mul_f32 v[48:49], v[48:49], s[98:99] op_sel_hi:[1,0]
	v_pk_mul_f32 v[50:51], v[50:51], s[98:99] op_sel_hi:[1,0]
	v_pk_mul_f32 v[44:45], v[44:45], s[98:99] op_sel_hi:[1,0]
	v_pk_mul_f32 v[46:47], v[46:47], s[98:99] op_sel_hi:[1,0]
	v_exp_f32_e32 v48, v48
	v_exp_f32_e32 v44, v44
	v_exp_f32_e32 v49, v49
	v_exp_f32_e32 v45, v45
	v_exp_f32_e32 v50, v50
	v_exp_f32_e32 v46, v46
	v_exp_f32_e32 v51, v51
	v_exp_f32_e32 v47, v47
	v_pk_add_f32 v[48:49], v[48:49], 1.0 op_sel_hi:[1,0]
	v_pk_add_f32 v[50:51], v[50:51], 1.0 op_sel_hi:[1,0]
	v_pk_add_f32 v[44:45], v[44:45], 1.0 op_sel_hi:[1,0]
	v_pk_add_f32 v[46:47], v[46:47], 1.0 op_sel_hi:[1,0]
	v_rcp_f32_e32 v48, v48
	v_rcp_f32_e32 v44, v44
; __device__ __forceinline__ float sigmoidf_(float x) { return __builtin_amdgcn_rcpf(1.0f + __expf(-x)); }
; __device__ __forceinline__ f32x4 sig4(const f32x4 v) { return (f32x4){sigmoidf_(v[0]), sigmoidf_(v[1]), sigmoidf_(v[2]), sigmoidf_(v[3])}; }
	v_rcp_f32_e32 v49, v49
	v_rcp_f32_e32 v45, v45
	v_rcp_f32_e32 v50, v50
	v_rcp_f32_e32 v46, v46
	v_rcp_f32_e32 v51, v51
	v_rcp_f32_e32 v47, v47
	v_pk_mul_f32 v[40:41], v[40:41], s[98:99] op_sel_hi:[1,0]
	v_pk_mul_f32 v[42:43], v[42:43], s[98:99] op_sel_hi:[1,0]
	v_pk_mul_f32 v[36:37], v[36:37], s[98:99] op_sel_hi:[1,0]
	v_pk_mul_f32 v[38:39], v[38:39], s[98:99] op_sel_hi:[1,0]
	v_exp_f32_e32 v40, v40
	v_exp_f32_e32 v36, v36
	v_exp_f32_e32 v41, v41
	v_exp_f32_e32 v37, v37
	v_exp_f32_e32 v42, v42
	v_exp_f32_e32 v38, v38
	v_exp_f32_e32 v43, v43
	v_exp_f32_e32 v39, v39
	v_pk_add_f32 v[40:41], v[40:41], 1.0 op_sel_hi:[1,0]
	v_pk_add_f32 v[42:43], v[42:43], 1.0 op_sel_hi:[1,0]
	v_pk_add_f32 v[36:37], v[36:37], 1.0 op_sel_hi:[1,0]
	v_pk_add_f32 v[38:39], v[38:39], 1.0 op_sel_hi:[1,0]
	v_rcp_f32_e32 v40, v40
	v_rcp_f32_e32 v36, v36
	v_rcp_f32_e32 v41, v41
	v_rcp_f32_e32 v37, v37
	v_rcp_f32_e32 v42, v42
	v_rcp_f32_e32 v38, v38
	v_rcp_f32_e32 v43, v43
	v_rcp_f32_e32 v39, v39
	v_pk_mul_f32 v[28:29], v[28:29], s[98:99] op_sel_hi:[1,0]
	v_pk_mul_f32 v[30:31], v[30:31], s[98:99] op_sel_hi:[1,0]
	v_pk_mul_f32 v[24:25], v[24:25], s[98:99] op_sel_hi:[1,0]
	v_pk_mul_f32 v[26:27], v[26:27], s[98:99] op_sel_hi:[1,0]
	v_exp_f32_e32 v28, v28
	v_exp_f32_e32 v24, v24
	v_exp_f32_e32 v29, v29
	v_exp_f32_e32 v25, v25
	v_exp_f32_e32 v30, v30
	v_exp_f32_e32 v26, v26
	v_exp_f32_e32 v31, v31
	v_exp_f32_e32 v27, v27
	v_pk_add_f32 v[28:29], v[28:29], 1.0 op_sel_hi:[1,0]
	v_pk_add_f32 v[30:31], v[30:31], 1.0 op_sel_hi:[1,0]
	v_pk_add_f32 v[24:25], v[24:25], 1.0 op_sel_hi:[1,0]
	v_pk_add_f32 v[26:27], v[26:27], 1.0 op_sel_hi:[1,0]
	v_rcp_f32_e32 v28, v28
	v_rcp_f32_e32 v24, v24
	v_rcp_f32_e32 v29, v29
	v_rcp_f32_e32 v25, v25
	v_rcp_f32_e32 v30, v30
	v_rcp_f32_e32 v26, v26
	v_rcp_f32_e32 v31, v31
	v_rcp_f32_e32 v27, v27
	v_pk_mul_f32 v[20:21], v[20:21], s[98:99] op_sel_hi:[1,0]
	v_pk_mul_f32 v[22:23], v[22:23], s[98:99] op_sel_hi:[1,0]
	v_pk_mul_f32 v[16:17], v[16:17], s[98:99] op_sel_hi:[1,0]
	v_pk_mul_f32 v[18:19], v[18:19], s[98:99] op_sel_hi:[1,0]
	v_exp_f32_e32 v20, v20
	v_exp_f32_e32 v16, v16
	v_exp_f32_e32 v21, v21
	v_exp_f32_e32 v17, v17
	v_exp_f32_e32 v22, v22
	v_exp_f32_e32 v18, v18
	v_exp_f32_e32 v23, v23
	v_exp_f32_e32 v19, v19
	v_pk_add_f32 v[20:21], v[20:21], 1.0 op_sel_hi:[1,0]
	v_pk_add_f32 v[22:23], v[22:23], 1.0 op_sel_hi:[1,0]
	v_pk_add_f32 v[16:17], v[16:17], 1.0 op_sel_hi:[1,0]
	v_pk_add_f32 v[18:19], v[18:19], 1.0 op_sel_hi:[1,0]
	v_rcp_f32_e32 v20, v20
	v_rcp_f32_e32 v16, v16
	v_rcp_f32_e32 v21, v21
	v_rcp_f32_e32 v17, v17
	v_rcp_f32_e32 v22, v22
	v_rcp_f32_e32 v18, v18
	v_rcp_f32_e32 v23, v23
	v_rcp_f32_e32 v19, v19
	v_pk_mul_f32 v[12:13], v[12:13], s[98:99] op_sel_hi:[1,0]
	v_pk_mul_f32 v[14:15], v[14:15], s[98:99] op_sel_hi:[1,0]
	v_pk_mul_f32 v[8:9], v[8:9], s[98:99] op_sel_hi:[1,0]
	v_pk_mul_f32 v[10:11], v[10:11], s[98:99] op_sel_hi:[1,0]
	v_exp_f32_e32 v12, v12
	v_exp_f32_e32 v8, v8
	v_exp_f32_e32 v13, v13
	v_exp_f32_e32 v9, v9
	v_exp_f32_e32 v14, v14
	v_exp_f32_e32 v10, v10
	v_exp_f32_e32 v15, v15
	v_exp_f32_e32 v11, v11
	v_pk_add_f32 v[12:13], v[12:13], 1.0 op_sel_hi:[1,0]
	v_pk_add_f32 v[14:15], v[14:15], 1.0 op_sel_hi:[1,0]
	v_pk_add_f32 v[8:9], v[8:9], 1.0 op_sel_hi:[1,0]
	v_pk_add_f32 v[10:11], v[10:11], 1.0 op_sel_hi:[1,0]
	v_rcp_f32_e32 v12, v12
	v_rcp_f32_e32 v8, v8
	v_rcp_f32_e32 v13, v13
	v_rcp_f32_e32 v9, v9
	v_rcp_f32_e32 v14, v14
	v_rcp_f32_e32 v10, v10
	v_rcp_f32_e32 v15, v15
	v_rcp_f32_e32 v11, v11
	v_pk_mul_f32 v[4:5], v[4:5], s[98:99] op_sel_hi:[1,0]
	v_pk_mul_f32 v[6:7], v[6:7], s[98:99] op_sel_hi:[1,0]
	v_pk_mul_f32 v[0:1], v[0:1], s[98:99] op_sel_hi:[1,0]
	v_pk_mul_f32 v[2:3], v[2:3], s[98:99] op_sel_hi:[1,0]
	v_exp_f32_e32 v4, v4
	v_exp_f32_e32 v0, v0
	v_exp_f32_e32 v5, v5
	v_exp_f32_e32 v1, v1
	v_exp_f32_e32 v6, v6
	v_exp_f32_e32 v2, v2
	v_exp_f32_e32 v7, v7
	v_exp_f32_e32 v3, v3
	v_pk_add_f32 v[4:5], v[4:5], 1.0 op_sel_hi:[1,0]
	v_pk_add_f32 v[6:7], v[6:7], 1.0 op_sel_hi:[1,0]
	v_pk_add_f32 v[0:1], v[0:1], 1.0 op_sel_hi:[1,0]
	v_pk_add_f32 v[2:3], v[2:3], 1.0 op_sel_hi:[1,0]
	v_rcp_f32_e32 v4, v4
	v_rcp_f32_e32 v0, v0
	v_rcp_f32_e32 v5, v5
	v_rcp_f32_e32 v1, v1
	v_rcp_f32_e32 v6, v6
	v_rcp_f32_e32 v2, v2
	v_rcp_f32_e32 v7, v7
	v_rcp_f32_e32 v3, v3
	s_waitcnt vmcnt(15)
	v_cvt_f32_f16_e32 v194, v136
	v_cvt_f32_f16_sdwa v195, v136 dst_sel:DWORD dst_unused:UNUSED_PAD src0_sel:WORD_1
	v_cvt_f32_f16_e32 v212, v137
	v_cvt_f32_f16_sdwa v213, v137 dst_sel:DWORD dst_unused:UNUSED_PAD src0_sel:WORD_1
	v_pk_mul_f32 v[128:129], v[128:129], v[194:195]
	v_cvt_f32_f16_e32 v194, v138
	v_cvt_f32_f16_sdwa v195, v138 dst_sel:DWORD dst_unused:UNUSED_PAD src0_sel:WORD_1
	v_pk_mul_f32 v[130:131], v[130:131], v[212:213]
	v_cvt_f32_f16_e32 v212, v139
	v_cvt_f32_f16_sdwa v213, v139 dst_sel:DWORD dst_unused:UNUSED_PAD src0_sel:WORD_1
	v_pk_mul_f32 v[124:125], v[124:125], v[194:195]
	s_waitcnt vmcnt(14)
	v_cvt_f32_f16_e32 v194, v140
	v_cvt_f32_f16_sdwa v195, v140 dst_sel:DWORD dst_unused:UNUSED_PAD src0_sel:WORD_1
	v_pk_mul_f32 v[126:127], v[126:127], v[212:213]
	v_cvt_f32_f16_e32 v212, v141
	v_cvt_f32_f16_sdwa v213, v141 dst_sel:DWORD dst_unused:UNUSED_PAD src0_sel:WORD_1
	v_pk_mul_f32 v[120:121], v[120:121], v[194:195]
	v_cvt_f32_f16_e32 v194, v142
	v_cvt_f32_f16_sdwa v195, v142 dst_sel:DWORD dst_unused:UNUSED_PAD src0_sel:WORD_1
	v_pk_mul_f32 v[122:123], v[122:123], v[212:213]
	v_cvt_f32_f16_e32 v212, v143
	v_cvt_f32_f16_sdwa v213, v143 dst_sel:DWORD dst_unused:UNUSED_PAD src0_sel:WORD_1
	v_pk_mul_f32 v[116:117], v[116:117], v[194:195]
	s_waitcnt vmcnt(13)
; __device__ __forceinline__ f32x4 sig4(const f32x4 v) { return (f32x4){sigmoidf_(v[0]), sigmoidf_(v[1]), sigmoidf_(v[2]), sigmoidf_(v[3])}; }
;     __device__ __forceinline__ void ple_gate(f32x4 (&acc)[2][2][4][2], const GUnit& u, int wr, int wc, int fr, int fq) const {
;     ...
; #pragma unroll
;         for (int ai = 0; ai < 2; ++ai)
; #pragma unroll
;             for (int m = 0; m < 4; ++m)
; #pragma unroll
;                 for (int bj = 0; bj < 2; ++bj) { f32x4 p0, p1; unpk8(pw[ai][m][bj], p0, p1); acc[ai][bj][m][0] = sig4(acc[ai][bj][m][0]) * p0; acc[ai][bj][m][1] = sig4(acc[ai][bj][m][1]) * p1; }
	v_cvt_f32_f16_e32 v194, v144
	v_cvt_f32_f16_sdwa v195, v144 dst_sel:DWORD dst_unused:UNUSED_PAD src0_sel:WORD_1
	v_pk_mul_f32 v[118:119], v[118:119], v[212:213]
	v_cvt_f32_f16_e32 v212, v145
	v_cvt_f32_f16_sdwa v213, v145 dst_sel:DWORD dst_unused:UNUSED_PAD src0_sel:WORD_1
	v_pk_mul_f32 v[112:113], v[112:113], v[194:195]
	v_cvt_f32_f16_e32 v194, v146
	v_cvt_f32_f16_sdwa v195, v146 dst_sel:DWORD dst_unused:UNUSED_PAD src0_sel:WORD_1
	v_pk_mul_f32 v[114:115], v[114:115], v[212:213]
	v_cvt_f32_f16_e32 v212, v147
	v_cvt_f32_f16_sdwa v213, v147 dst_sel:DWORD dst_unused:UNUSED_PAD src0_sel:WORD_1
	v_pk_mul_f32 v[108:109], v[108:109], v[194:195]
	s_waitcnt vmcnt(12)
	v_cvt_f32_f16_e32 v194, v148
	v_cvt_f32_f16_sdwa v195, v148 dst_sel:DWORD dst_unused:UNUSED_PAD src0_sel:WORD_1
	v_pk_mul_f32 v[110:111], v[110:111], v[212:213]
	v_cvt_f32_f16_e32 v212, v149
	v_cvt_f32_f16_sdwa v213, v149 dst_sel:DWORD dst_unused:UNUSED_PAD src0_sel:WORD_1
	v_pk_mul_f32 v[104:105], v[104:105], v[194:195]
	v_cvt_f32_f16_e32 v194, v150
	v_cvt_f32_f16_sdwa v195, v150 dst_sel:DWORD dst_unused:UNUSED_PAD src0_sel:WORD_1
	v_pk_mul_f32 v[106:107], v[106:107], v[212:213]
	v_cvt_f32_f16_e32 v212, v151
	v_cvt_f32_f16_sdwa v213, v151 dst_sel:DWORD dst_unused:UNUSED_PAD src0_sel:WORD_1
	v_pk_mul_f32 v[100:101], v[100:101], v[194:195]
	s_waitcnt vmcnt(11)
	v_cvt_f32_f16_e32 v194, v152
	v_cvt_f32_f16_sdwa v195, v152 dst_sel:DWORD dst_unused:UNUSED_PAD src0_sel:WORD_1
	v_pk_mul_f32 v[102:103], v[102:103], v[212:213]
	v_cvt_f32_f16_e32 v212, v153
	v_cvt_f32_f16_sdwa v213, v153 dst_sel:DWORD dst_unused:UNUSED_PAD src0_sel:WORD_1
	v_pk_mul_f32 v[96:97], v[96:97], v[194:195]
	v_cvt_f32_f16_e32 v194, v154
	v_cvt_f32_f16_sdwa v195, v154 dst_sel:DWORD dst_unused:UNUSED_PAD src0_sel:WORD_1
	v_pk_mul_f32 v[98:99], v[98:99], v[212:213]
	v_cvt_f32_f16_e32 v212, v155
	v_cvt_f32_f16_sdwa v213, v155 dst_sel:DWORD dst_unused:UNUSED_PAD src0_sel:WORD_1
	v_pk_mul_f32 v[92:93], v[92:93], v[194:195]
	s_waitcnt vmcnt(10)
	v_cvt_f32_f16_e32 v194, v156
	v_cvt_f32_f16_sdwa v195, v156 dst_sel:DWORD dst_unused:UNUSED_PAD src0_sel:WORD_1
	v_pk_mul_f32 v[94:95], v[94:95], v[212:213]
	v_cvt_f32_f16_e32 v212, v157
	v_cvt_f32_f16_sdwa v213, v157 dst_sel:DWORD dst_unused:UNUSED_PAD src0_sel:WORD_1
	v_pk_mul_f32 v[88:89], v[88:89], v[194:195]
	v_cvt_f32_f16_e32 v194, v158
	v_cvt_f32_f16_sdwa v195, v158 dst_sel:DWORD dst_unused:UNUSED_PAD src0_sel:WORD_1
	v_pk_mul_f32 v[90:91], v[90:91], v[212:213]
	v_cvt_f32_f16_e32 v212, v159
	v_cvt_f32_f16_sdwa v213, v159 dst_sel:DWORD dst_unused:UNUSED_PAD src0_sel:WORD_1
	v_pk_mul_f32 v[84:85], v[84:85], v[194:195]
	s_waitcnt vmcnt(9)
	v_cvt_f32_f16_e32 v194, v160
	v_cvt_f32_f16_sdwa v195, v160 dst_sel:DWORD dst_unused:UNUSED_PAD src0_sel:WORD_1
	v_pk_mul_f32 v[86:87], v[86:87], v[212:213]
	v_cvt_f32_f16_e32 v212, v161
	v_cvt_f32_f16_sdwa v213, v161 dst_sel:DWORD dst_unused:UNUSED_PAD src0_sel:WORD_1
	v_pk_mul_f32 v[80:81], v[80:81], v[194:195]
	v_cvt_f32_f16_e32 v194, v162
	v_cvt_f32_f16_sdwa v195, v162 dst_sel:DWORD dst_unused:UNUSED_PAD src0_sel:WORD_1
	v_pk_mul_f32 v[82:83], v[82:83], v[212:213]
	v_cvt_f32_f16_e32 v212, v163
	v_cvt_f32_f16_sdwa v213, v163 dst_sel:DWORD dst_unused:UNUSED_PAD src0_sel:WORD_1
	v_pk_mul_f32 v[76:77], v[76:77], v[194:195]
	s_waitcnt vmcnt(8)
	v_cvt_f32_f16_e32 v194, v164
	v_cvt_f32_f16_sdwa v195, v164 dst_sel:DWORD dst_unused:UNUSED_PAD src0_sel:WORD_1
	v_pk_mul_f32 v[78:79], v[78:79], v[212:213]
	v_cvt_f32_f16_e32 v212, v165
	v_cvt_f32_f16_sdwa v213, v165 dst_sel:DWORD dst_unused:UNUSED_PAD src0_sel:WORD_1
	v_pk_mul_f32 v[72:73], v[72:73], v[194:195]
	v_cvt_f32_f16_e32 v194, v166
	v_cvt_f32_f16_sdwa v195, v166 dst_sel:DWORD dst_unused:UNUSED_PAD src0_sel:WORD_1
	v_pk_mul_f32 v[74:75], v[74:75], v[212:213]
	v_cvt_f32_f16_e32 v212, v167
	v_cvt_f32_f16_sdwa v213, v167 dst_sel:DWORD dst_unused:UNUSED_PAD src0_sel:WORD_1
	v_pk_mul_f32 v[68:69], v[68:69], v[194:195]
	s_waitcnt vmcnt(7)
	v_cvt_f32_f16_e32 v194, v168
	v_cvt_f32_f16_sdwa v195, v168 dst_sel:DWORD dst_unused:UNUSED_PAD src0_sel:WORD_1
	v_pk_mul_f32 v[70:71], v[70:71], v[212:213]
	v_cvt_f32_f16_e32 v212, v169
	v_cvt_f32_f16_sdwa v213, v169 dst_sel:DWORD dst_unused:UNUSED_PAD src0_sel:WORD_1
	v_pk_mul_f32 v[64:65], v[64:65], v[194:195]
	v_cvt_f32_f16_e32 v194, v170
	v_cvt_f32_f16_sdwa v195, v170 dst_sel:DWORD dst_unused:UNUSED_PAD src0_sel:WORD_1
	v_pk_mul_f32 v[66:67], v[66:67], v[212:213]
	v_cvt_f32_f16_e32 v212, v171
	v_cvt_f32_f16_sdwa v213, v171 dst_sel:DWORD dst_unused:UNUSED_PAD src0_sel:WORD_1
	v_pk_mul_f32 v[60:61], v[60:61], v[194:195]
	s_waitcnt vmcnt(6)
; __device__ __forceinline__ f32x4 sig4(const f32x4 v) { return (f32x4){sigmoidf_(v[0]), sigmoidf_(v[1]), sigmoidf_(v[2]), sigmoidf_(v[3])}; }
;     __device__ __forceinline__ void ple_gate(f32x4 (&acc)[2][2][4][2], const GUnit& u, int wr, int wc, int fr, int fq) const {
;     ...
; #pragma unroll
;         for (int ai = 0; ai < 2; ++ai)
; #pragma unroll
;             for (int m = 0; m < 4; ++m)
; #pragma unroll
;                 for (int bj = 0; bj < 2; ++bj) { f32x4 p0, p1; unpk8(pw[ai][m][bj], p0, p1); acc[ai][bj][m][0] = sig4(acc[ai][bj][m][0]) * p0; acc[ai][bj][m][1] = sig4(acc[ai][bj][m][1]) * p1; }
	v_cvt_f32_f16_e32 v194, v172
	v_cvt_f32_f16_sdwa v195, v172 dst_sel:DWORD dst_unused:UNUSED_PAD src0_sel:WORD_1
	v_pk_mul_f32 v[62:63], v[62:63], v[212:213]
	v_cvt_f32_f16_e32 v212, v173
	v_cvt_f32_f16_sdwa v213, v173 dst_sel:DWORD dst_unused:UNUSED_PAD src0_sel:WORD_1
	v_pk_mul_f32 v[56:57], v[56:57], v[194:195]
	v_cvt_f32_f16_e32 v194, v174
	v_cvt_f32_f16_sdwa v195, v174 dst_sel:DWORD dst_unused:UNUSED_PAD src0_sel:WORD_1
	v_pk_mul_f32 v[58:59], v[58:59], v[212:213]
	v_cvt_f32_f16_e32 v212, v175
	v_cvt_f32_f16_sdwa v213, v175 dst_sel:DWORD dst_unused:UNUSED_PAD src0_sel:WORD_1
	v_pk_mul_f32 v[52:53], v[52:53], v[194:195]
	s_waitcnt vmcnt(5)
	v_cvt_f32_f16_e32 v194, v176
	v_cvt_f32_f16_sdwa v195, v176 dst_sel:DWORD dst_unused:UNUSED_PAD src0_sel:WORD_1
	v_pk_mul_f32 v[54:55], v[54:55], v[212:213]
	v_cvt_f32_f16_e32 v212, v177
	v_cvt_f32_f16_sdwa v213, v177 dst_sel:DWORD dst_unused:UNUSED_PAD src0_sel:WORD_1
	v_pk_mul_f32 v[48:49], v[48:49], v[194:195]
	v_cvt_f32_f16_e32 v194, v178
	v_cvt_f32_f16_sdwa v195, v178 dst_sel:DWORD dst_unused:UNUSED_PAD src0_sel:WORD_1
	v_pk_mul_f32 v[50:51], v[50:51], v[212:213]
	v_cvt_f32_f16_e32 v212, v179
	v_cvt_f32_f16_sdwa v213, v179 dst_sel:DWORD dst_unused:UNUSED_PAD src0_sel:WORD_1
	v_pk_mul_f32 v[44:45], v[44:45], v[194:195]
	s_waitcnt vmcnt(4)
	v_cvt_f32_f16_e32 v194, v180
	v_cvt_f32_f16_sdwa v195, v180 dst_sel:DWORD dst_unused:UNUSED_PAD src0_sel:WORD_1
	v_pk_mul_f32 v[46:47], v[46:47], v[212:213]
	v_cvt_f32_f16_e32 v212, v181
	v_cvt_f32_f16_sdwa v213, v181 dst_sel:DWORD dst_unused:UNUSED_PAD src0_sel:WORD_1
	v_pk_mul_f32 v[40:41], v[40:41], v[194:195]
	v_cvt_f32_f16_e32 v194, v182
	v_cvt_f32_f16_sdwa v195, v182 dst_sel:DWORD dst_unused:UNUSED_PAD src0_sel:WORD_1
	v_pk_mul_f32 v[42:43], v[42:43], v[212:213]
	v_cvt_f32_f16_e32 v212, v183
	v_cvt_f32_f16_sdwa v213, v183 dst_sel:DWORD dst_unused:UNUSED_PAD src0_sel:WORD_1
	v_pk_mul_f32 v[36:37], v[36:37], v[194:195]
	s_waitcnt vmcnt(3)
	v_cvt_f32_f16_e32 v194, v190
	v_cvt_f32_f16_sdwa v195, v190 dst_sel:DWORD dst_unused:UNUSED_PAD src0_sel:WORD_1
	v_pk_mul_f32 v[38:39], v[38:39], v[212:213]
	v_cvt_f32_f16_e32 v212, v191
	v_cvt_f32_f16_sdwa v213, v191 dst_sel:DWORD dst_unused:UNUSED_PAD src0_sel:WORD_1
	v_pk_mul_f32 v[28:29], v[28:29], v[194:195]
	v_cvt_f32_f16_e32 v194, v192
	v_cvt_f32_f16_sdwa v195, v192 dst_sel:DWORD dst_unused:UNUSED_PAD src0_sel:WORD_1
	v_pk_mul_f32 v[30:31], v[30:31], v[212:213]
	v_cvt_f32_f16_e32 v212, v193
	v_cvt_f32_f16_sdwa v213, v193 dst_sel:DWORD dst_unused:UNUSED_PAD src0_sel:WORD_1
	v_pk_mul_f32 v[24:25], v[24:25], v[194:195]
	s_waitcnt vmcnt(2)
	v_cvt_f32_f16_e32 v194, v198
	v_cvt_f32_f16_sdwa v195, v198 dst_sel:DWORD dst_unused:UNUSED_PAD src0_sel:WORD_1
	v_pk_mul_f32 v[26:27], v[26:27], v[212:213]
	v_cvt_f32_f16_e32 v212, v199
	v_cvt_f32_f16_sdwa v213, v199 dst_sel:DWORD dst_unused:UNUSED_PAD src0_sel:WORD_1
	v_pk_mul_f32 v[20:21], v[20:21], v[194:195]
	v_cvt_f32_f16_e32 v194, v200
	v_cvt_f32_f16_sdwa v195, v200 dst_sel:DWORD dst_unused:UNUSED_PAD src0_sel:WORD_1
	v_pk_mul_f32 v[22:23], v[22:23], v[212:213]
	v_cvt_f32_f16_e32 v212, v201
	v_cvt_f32_f16_sdwa v213, v201 dst_sel:DWORD dst_unused:UNUSED_PAD src0_sel:WORD_1
	v_pk_mul_f32 v[16:17], v[16:17], v[194:195]
	s_waitcnt vmcnt(1)
	v_cvt_f32_f16_e32 v194, v204
	v_cvt_f32_f16_sdwa v195, v204 dst_sel:DWORD dst_unused:UNUSED_PAD src0_sel:WORD_1
	v_pk_mul_f32 v[18:19], v[18:19], v[212:213]
	v_cvt_f32_f16_e32 v212, v205
	v_cvt_f32_f16_sdwa v213, v205 dst_sel:DWORD dst_unused:UNUSED_PAD src0_sel:WORD_1
	v_pk_mul_f32 v[12:13], v[12:13], v[194:195]
	v_cvt_f32_f16_e32 v194, v206
	v_cvt_f32_f16_sdwa v195, v206 dst_sel:DWORD dst_unused:UNUSED_PAD src0_sel:WORD_1
	v_pk_mul_f32 v[14:15], v[14:15], v[212:213]
	v_cvt_f32_f16_e32 v212, v207
	v_cvt_f32_f16_sdwa v213, v207 dst_sel:DWORD dst_unused:UNUSED_PAD src0_sel:WORD_1
	v_pk_mul_f32 v[8:9], v[8:9], v[194:195]
	s_waitcnt vmcnt(0)
	v_cvt_f32_f16_e32 v194, v208
	v_cvt_f32_f16_sdwa v195, v208 dst_sel:DWORD dst_unused:UNUSED_PAD src0_sel:WORD_1
	v_pk_mul_f32 v[10:11], v[10:11], v[212:213]
	v_cvt_f32_f16_e32 v212, v209
	v_cvt_f32_f16_sdwa v213, v209 dst_sel:DWORD dst_unused:UNUSED_PAD src0_sel:WORD_1
	v_pk_mul_f32 v[4:5], v[4:5], v[194:195]
	v_cvt_f32_f16_e32 v194, v210
	v_cvt_f32_f16_sdwa v195, v210 dst_sel:DWORD dst_unused:UNUSED_PAD src0_sel:WORD_1
	v_pk_mul_f32 v[6:7], v[6:7], v[212:213]
	v_cvt_f32_f16_e32 v212, v211
	v_cvt_f32_f16_sdwa v213, v211 dst_sel:DWORD dst_unused:UNUSED_PAD src0_sel:WORD_1
	v_pk_mul_f32 v[0:1], v[0:1], v[194:195]
	v_pk_mul_f32 v[2:3], v[2:3], v[212:213]
	s_andn2_b64 vcc, exec, s[30:31]
	s_cbranch_vccz .LBB0_222
